# plus w_down epilogue: residual rows requested one row-group pair ahead
# baseline (speedup 1.0000x reference)
;     __device__ __forceinline__ void operator()(const f32x4 (&acc)[2][2][4][2], const Unit& u, int wr, int wc, int fr, int fq) const {
;     ...
;                 for (int mm = 0; mm < NPF; ++mm) { const int row = row0 + ai * HALF + (NPF * mp + mm) * 16;
; #pragma unroll
;                     for (int bj = 0; bj < 2; ++bj) { const size_t off = (size_t)row * 1024 + col0 + bj * HALF; hv[mm][bj] = *(const u32x4*)(hin + off); if (GATED) pv[mm][bj] = *(const u32x4*)(pl + off); } }
; #pragma unroll
;                 for (int mm = 0; mm < NPF; ++mm) { const int m = NPF * mp + mm, row = row0 + ai * HALF + m * 16;
;                     float r = 1.f; if (GATED) r = (u.ui < 8) ? rtab[u.ui * 256 + wr * 64 + fr + ai * HALF + m * 16] : rinv16(ssq_in, row, 1.0f / 1024.0f);
;                     if (MID) r = rtab[u.ui * 512 + wr * 64 + fr + ai * HALF + m * 16];
;                     float sq = 0.f;
; #pragma unroll
;                     for (int bj = 0; bj < 2; ++bj) { const size_t off = (size_t)row * 1024 + col0 + bj * HALF;
;                         f32x4 a0 = acc[ai][bj][m][0], a1 = acc[ai][bj][m][1]; const u32x4 hq = hv[mm][bj];
;                         f32x4 x0 = (f32x4){bf_lo(hq.x), bf_hi(hq.x), bf_lo(hq.y), bf_hi(hq.y)}, x1 = (f32x4){bf_lo(hq.z), bf_hi(hq.z), bf_lo(hq.w), bf_hi(hq.w)};
;                         if (MID) { a0 = a0 * r; a1 = a1 * r; }
;                         if (GATED) { const u32x4 p4 = pv[mm][bj];
;                             a0[0] = sigmoid_f(a0[0] * r) * bf_lo(p4.x); a0[1] = sigmoid_f(a0[1] * r) * bf_hi(p4.x); a0[2] = sigmoid_f(a0[2] * r) * bf_lo(p4.y); a0[3] = sigmoid_f(a0[3] * r) * bf_hi(p4.y);
;                             a1[0] = sigmoid_f(a1[0] * r) * bf_lo(p4.z); a1[1] = sigmoid_f(a1[1] * r) * bf_hi(p4.z); a1[2] = sigmoid_f(a1[2] * r) * bf_lo(p4.w); a1[3] = sigmoid_f(a1[3] * r) * bf_hi(p4.w); }
;                         x0 = x0 + a0; x1 = x1 + a1;
;                         u32x4 w; w.x = cvt_pk_bf16(x0[0], x0[1]); w.y = cvt_pk_bf16(x0[2], x0[3]); w.z = cvt_pk_bf16(x1[0], x1[1]); w.w = cvt_pk_bf16(x1[2], x1[3]);
;                         if (!dry) *(u32x4*)(hb + off) = w; else asm volatile("" :: "v"(w.x), "v"(w.y), "v"(w.z), "v"(w.w));
;                         sq += ((x0[0] * x0[0] + x0[1] * x0[1]) + (x0[2] * x0[2] + x0[3] * x0[3])) + ((x1[0] * x1[0] + x1[1] * x1[1]) + (x1[2] * x1[2] + x1[3] * x1[3])); }
.LBB0_1671:
	s_mov_b32 s0, s57
	s_mov_b32 s1, s70
	v_lshl_or_b32 v2, s71, 6, v237
	v_lshl_or_b32 v4, s0, 8, v239
	v_lshl_add_u32 v150, s1, 8, v2
	v_ashrrev_i32_e32 v5, 31, v4
	v_lshlrev_b64 v[166:167], 1, v[4:5]
	v_ashrrev_i32_e32 v151, 31, v150
	v_lshl_add_u64 v[152:153], s[14:15], 0, v[166:167]
	v_lshlrev_b64 v[168:169], 11, v[150:151]
	v_lshl_add_u64 v[142:143], v[152:153], 0, v[168:169]
	global_load_dwordx4 v[158:161], v[142:143], off
	global_load_dwordx4 v[162:165], v[142:143], off offset:256
	v_or_b32_e32 v154, 16, v150
	v_ashrrev_i32_e32 v155, 31, v154
	v_lshlrev_b64 v[156:157], 11, v[154:155]
	v_lshl_add_u64 v[142:143], v[152:153], 0, v[156:157]
	global_load_dwordx4 v[146:149], v[142:143], off
	s_nop 0
	global_load_dwordx4 v[142:145], v[142:143], off offset:256
	v_add_u32_e32 v196, 32, v150
	v_ashrrev_i32_e32 v197, 31, v196
	v_lshlrev_b64 v[196:197], 11, v[196:197]
	v_lshl_add_u64 v[196:197], v[152:153], 0, v[196:197]
	global_load_dwordx4 v[180:183], v[196:197], off
	global_load_dwordx4 v[184:187], v[196:197], off offset:256
	v_add_u32_e32 v198, 48, v150
	v_ashrrev_i32_e32 v199, 31, v198
	v_lshlrev_b64 v[198:199], 11, v[198:199]
	v_lshl_add_u64 v[198:199], v[152:153], 0, v[198:199]
	global_load_dwordx4 v[188:191], v[198:199], off
	global_load_dwordx4 v[192:195], v[198:199], off offset:256
	v_lshl_add_u64 v[168:169], s[14:15], 0, v[168:169]
	v_lshl_add_u64 v[166:167], v[168:169], 0, v[166:167]
	s_lshl_b32 s6, s0, 2
	s_ashr_i32 s7, s6, 31
	s_waitcnt vmcnt(4)
	v_lshlrev_b32_e32 v170, 16, v158
	v_and_b32_e32 v171, 0xffff0000, v158
	v_lshlrev_b32_e32 v158, 16, v159
	v_and_b32_e32 v159, 0xffff0000, v159
	v_lshlrev_b32_e32 v172, 16, v160
	v_and_b32_e32 v173, 0xffff0000, v160
	v_lshlrev_b32_e32 v160, 16, v161
	v_and_b32_e32 v161, 0xffff0000, v161
	v_pk_add_f32 v[140:141], v[140:141], v[158:159]
	v_pk_add_f32 v[138:139], v[138:139], v[170:171]
	v_pk_add_f32 v[158:159], v[136:137], v[160:161]
	v_pk_add_f32 v[160:161], v[134:135], v[172:173]
	v_cvt_pk_bf16_f32 v134, v138, v139
	v_cvt_pk_bf16_f32 v135, v140, v141
	v_mul_f32_e32 v2, v139, v139
	v_cvt_pk_bf16_f32 v136, v160, v161
	v_cvt_pk_bf16_f32 v137, v158, v159
	global_store_dwordx4 v[166:167], v[134:137], off
	v_fmac_f32_e32 v2, v138, v138
	v_lshlrev_b32_e32 v138, 16, v164
	v_mul_f32_e32 v134, v141, v141
	v_fmac_f32_e32 v134, v140, v140
	v_add_f32_e32 v2, v2, v134
	v_mul_f32_e32 v134, v161, v161
	v_mul_f32_e32 v135, v159, v159
	v_fmac_f32_e32 v134, v160, v160
	v_fmac_f32_e32 v135, v158, v158
	v_add_f32_e32 v134, v134, v135
	v_add_f32_e32 v2, v2, v134
	v_lshlrev_b32_e32 v134, 16, v162
	v_and_b32_e32 v135, 0xffff0000, v162
	v_lshlrev_b32_e32 v136, 16, v163
	v_and_b32_e32 v137, 0xffff0000, v163
	v_and_b32_e32 v139, 0xffff0000, v164
	v_lshlrev_b32_e32 v140, 16, v165
	v_and_b32_e32 v141, 0xffff0000, v165
	v_pk_add_f32 v[132:133], v[132:133], v[136:137]
	v_pk_add_f32 v[130:131], v[130:131], v[134:135]
	v_pk_add_f32 v[136:137], v[126:127], v[138:139]
	v_cvt_pk_bf16_f32 v126, v130, v131
	v_cvt_pk_bf16_f32 v127, v132, v133
	v_pk_add_f32 v[134:135], v[128:129], v[140:141]
	v_cvt_pk_bf16_f32 v128, v136, v137
	s_nop 0
	v_cvt_pk_bf16_f32 v129, v134, v135
	global_store_dwordx4 v[166:167], v[126:129], off offset:256
	s_nop 1
	v_mul_f32_e32 v126, v131, v131
	v_mul_f32_e32 v127, v133, v133
	v_fmac_f32_e32 v126, v130, v130
	v_fmac_f32_e32 v127, v132, v132
	v_add_f32_e32 v126, v126, v127
	v_mul_f32_e32 v127, v137, v137
	v_mul_f32_e32 v128, v135, v135
	v_fmac_f32_e32 v127, v136, v136
	v_fmac_f32_e32 v128, v134, v134
	v_add_f32_e32 v127, v127, v128
	v_add_f32_e32 v126, v126, v127
	v_add_f32_e32 v2, v2, v126
	v_mov_b32_e32 v126, v2
	v_mov_b32_e32 v127, v2
	v_and_b32_e32 v128, 16, v247
	s_nop 0
	v_permlane16_swap_b32_e32 v126, v127
	v_cmp_eq_u32_e64 s[0:1], 0, v128
	s_nop 1
	v_cndmask_b32_e64 v126, v126, v127, s[0:1]
	v_add_f32_e32 v2, v2, v126
	v_mov_b32_e32 v126, v2
	v_mov_b32_e32 v127, v2
	s_nop 1
	v_permlane32_swap_b32_e32 v126, v127
	s_and_saveexec_b64 s[34:35], s[2:3]
	s_cbranch_execz .LBB0_1673
	v_and_b32_e32 v128, 32, v247
	v_cmp_eq_u32_e32 vcc, 0, v128
	s_lshl_b32 s84, s81, 2
	s_nop 0
	v_cndmask_b32_e32 v126, v126, v127, vcc
	v_add_f32_e32 v2, v2, v126
	v_lshlrev_b64 v[126:127], 6, v[150:151]
	v_lshl_add_u64 v[126:127], s[16:17], 0, v[126:127]
	v_lshl_add_u64 v[126:127], s[6:7], 2, v[126:127]
	v_lshl_add_u64 v[126:127], v[126:127], 0, s[84:85]
	global_store_dword v[126:127], v2, off

;     __device__ __forceinline__ void operator()(const f32x4 (&acc)[2][2][4][2], const Unit& u, int wr, int wc, int fr, int fq) const {
;     ...
;                 for (int mm = 0; mm < NPF; ++mm) { const int row = row0 + ai * HALF + (NPF * mp + mm) * 16;
; #pragma unroll
;                     for (int bj = 0; bj < 2; ++bj) { const size_t off = (size_t)row * 1024 + col0 + bj * HALF; hv[mm][bj] = *(const u32x4*)(hin + off); if (GATED) pv[mm][bj] = *(const u32x4*)(pl + off); } }
; #pragma unroll
;                 for (int mm = 0; mm < NPF; ++mm) { const int m = NPF * mp + mm, row = row0 + ai * HALF + m * 16;
;                     float r = 1.f; if (GATED) r = (u.ui < 8) ? rtab[u.ui * 256 + wr * 64 + fr + ai * HALF + m * 16] : rinv16(ssq_in, row, 1.0f / 1024.0f);
;                     if (MID) r = rtab[u.ui * 512 + wr * 64 + fr + ai * HALF + m * 16];
;                     float sq = 0.f;
; #pragma unroll
;                     for (int bj = 0; bj < 2; ++bj) { const size_t off = (size_t)row * 1024 + col0 + bj * HALF;
;                         f32x4 a0 = acc[ai][bj][m][0], a1 = acc[ai][bj][m][1]; const u32x4 hq = hv[mm][bj];
;                         f32x4 x0 = (f32x4){bf_lo(hq.x), bf_hi(hq.x), bf_lo(hq.y), bf_hi(hq.y)}, x1 = (f32x4){bf_lo(hq.z), bf_hi(hq.z), bf_lo(hq.w), bf_hi(hq.w)};
;                         if (MID) { a0 = a0 * r; a1 = a1 * r; }
;                         if (GATED) { const u32x4 p4 = pv[mm][bj];
;                             a0[0] = sigmoid_f(a0[0] * r) * bf_lo(p4.x); a0[1] = sigmoid_f(a0[1] * r) * bf_hi(p4.x); a0[2] = sigmoid_f(a0[2] * r) * bf_lo(p4.y); a0[3] = sigmoid_f(a0[3] * r) * bf_hi(p4.y);
;                             a1[0] = sigmoid_f(a1[0] * r) * bf_lo(p4.z); a1[1] = sigmoid_f(a1[1] * r) * bf_hi(p4.z); a1[2] = sigmoid_f(a1[2] * r) * bf_lo(p4.w); a1[3] = sigmoid_f(a1[3] * r) * bf_hi(p4.w); }
;                         x0 = x0 + a0; x1 = x1 + a1;
;                         u32x4 w; w.x = cvt_pk_bf16(x0[0], x0[1]); w.y = cvt_pk_bf16(x0[2], x0[3]); w.z = cvt_pk_bf16(x1[0], x1[1]); w.w = cvt_pk_bf16(x1[2], x1[3]);
;                         if (!dry) *(u32x4*)(hb + off) = w; else asm volatile("" :: "v"(w.x), "v"(w.y), "v"(w.z), "v"(w.w));
;                         sq += ((x0[0] * x0[0] + x0[1] * x0[1]) + (x0[2] * x0[2] + x0[3] * x0[3])) + ((x1[0] * x1[0] + x1[1] * x1[1]) + (x1[2] * x1[2] + x1[3] * x1[3])); }
.LBB0_1675:
	s_or_b64 exec, exec, s[34:35]
	v_or_b32_e32 v122, 32, v150
	v_ashrrev_i32_e32 v123, 31, v122
	v_lshlrev_b64 v[132:133], 11, v[122:123]
	v_lshl_add_u64 v[110:111], v[152:153], 0, v[132:133]
	v_or_b32_e32 v118, 48, v150
	v_ashrrev_i32_e32 v119, 31, v118
	v_lshlrev_b64 v[120:121], 11, v[118:119]
	v_lshl_add_u64 v[110:111], v[152:153], 0, v[120:121]
	v_lshl_add_u64 v[132:133], s[14:15], 0, v[132:133]
	v_lshl_add_u64 v[132:133], v[4:5], 1, v[132:133]
	s_waitcnt vmcnt(6)
	v_mov_b64_e32 v[124:125], v[180:181]
	v_mov_b64_e32 v[126:127], v[182:183]
	v_mov_b64_e32 v[128:129], v[184:185]
	v_mov_b64_e32 v[130:131], v[186:187]
	v_mov_b64_e32 v[114:115], v[188:189]
	v_mov_b64_e32 v[116:117], v[190:191]
	v_mov_b64_e32 v[110:111], v[192:193]
	v_mov_b64_e32 v[112:113], v[194:195]
	v_add_u32_e32 v196, 128, v150
	v_ashrrev_i32_e32 v197, 31, v196
	v_lshlrev_b64 v[196:197], 11, v[196:197]
	v_lshl_add_u64 v[196:197], v[152:153], 0, v[196:197]
	global_load_dwordx4 v[180:183], v[196:197], off
	global_load_dwordx4 v[184:187], v[196:197], off offset:256
	v_add_u32_e32 v198, 144, v150
	v_ashrrev_i32_e32 v199, 31, v198
	v_lshlrev_b64 v[198:199], 11, v[198:199]
	v_lshl_add_u64 v[198:199], v[152:153], 0, v[198:199]
	global_load_dwordx4 v[188:191], v[198:199], off
	global_load_dwordx4 v[192:195], v[198:199], off offset:256
	v_lshlrev_b32_e32 v134, 16, v124
	v_and_b32_e32 v135, 0xffff0000, v124
	v_lshlrev_b32_e32 v124, 16, v125
	v_and_b32_e32 v125, 0xffff0000, v125
	v_lshlrev_b32_e32 v136, 16, v126
	v_and_b32_e32 v137, 0xffff0000, v126
	v_lshlrev_b32_e32 v126, 16, v127
	v_and_b32_e32 v127, 0xffff0000, v127
	v_pk_add_f32 v[108:109], v[108:109], v[124:125]
	v_pk_add_f32 v[106:107], v[106:107], v[134:135]
	v_pk_add_f32 v[124:125], v[104:105], v[126:127]
	v_pk_add_f32 v[126:127], v[102:103], v[136:137]
	v_cvt_pk_bf16_f32 v102, v106, v107
	v_cvt_pk_bf16_f32 v103, v108, v109
	v_mul_f32_e32 v2, v107, v107
	v_cvt_pk_bf16_f32 v104, v126, v127
	v_cvt_pk_bf16_f32 v105, v124, v125
	global_store_dwordx4 v[132:133], v[102:105], off
	v_fmac_f32_e32 v2, v106, v106
	v_lshlrev_b32_e32 v106, 16, v130
	v_mul_f32_e32 v102, v109, v109
	v_fmac_f32_e32 v102, v108, v108
	v_add_f32_e32 v2, v2, v102
	v_mul_f32_e32 v102, v127, v127
	v_mul_f32_e32 v103, v125, v125
	v_fmac_f32_e32 v102, v126, v126
	v_fmac_f32_e32 v103, v124, v124
	v_add_f32_e32 v102, v102, v103
	v_add_f32_e32 v2, v2, v102
	v_lshlrev_b32_e32 v102, 16, v128
	v_and_b32_e32 v103, 0xffff0000, v128
	v_lshlrev_b32_e32 v104, 16, v129
	v_and_b32_e32 v105, 0xffff0000, v129
	v_and_b32_e32 v107, 0xffff0000, v130
	v_lshlrev_b32_e32 v108, 16, v131
	v_and_b32_e32 v109, 0xffff0000, v131
	v_pk_add_f32 v[100:101], v[100:101], v[104:105]
	v_pk_add_f32 v[98:99], v[98:99], v[102:103]
	v_pk_add_f32 v[104:105], v[94:95], v[106:107]
	v_cvt_pk_bf16_f32 v94, v98, v99
	v_cvt_pk_bf16_f32 v95, v100, v101
	v_pk_add_f32 v[102:103], v[96:97], v[108:109]
	v_cvt_pk_bf16_f32 v96, v104, v105
	s_nop 0
	v_cvt_pk_bf16_f32 v97, v102, v103
	global_store_dwordx4 v[132:133], v[94:97], off offset:256
	s_nop 1
	v_mul_f32_e32 v94, v99, v99
	v_mul_f32_e32 v95, v101, v101
	v_fmac_f32_e32 v94, v98, v98
	v_fmac_f32_e32 v95, v100, v100
	v_add_f32_e32 v94, v94, v95
	v_mul_f32_e32 v95, v105, v105
	v_mul_f32_e32 v96, v103, v103
	v_fmac_f32_e32 v95, v104, v104
	v_fmac_f32_e32 v96, v102, v102
	v_add_f32_e32 v95, v95, v96
	v_add_f32_e32 v94, v94, v95
	v_add_f32_e32 v2, v2, v94
	v_mov_b32_e32 v94, v2
	v_mov_b32_e32 v95, v2
	s_nop 1
	v_permlane16_swap_b32_e32 v94, v95
	v_cndmask_b32_e64 v94, v94, v95, s[0:1]
	v_add_f32_e32 v2, v2, v94
	v_mov_b32_e32 v94, v2
	v_mov_b32_e32 v95, v2
	s_nop 1
	v_permlane32_swap_b32_e32 v94, v95
	s_and_saveexec_b64 s[34:35], s[2:3]
	s_cbranch_execz .LBB0_1677
	v_and_b32_e32 v96, 32, v247
	v_cmp_eq_u32_e32 vcc, 0, v96
	s_lshl_b32 s84, s81, 2
	s_nop 0
	v_cndmask_b32_e32 v94, v94, v95, vcc
	v_add_f32_e32 v2, v2, v94
	v_lshlrev_b64 v[94:95], 6, v[122:123]
	v_lshl_add_u64 v[94:95], s[16:17], 0, v[94:95]
	v_lshl_add_u64 v[94:95], s[6:7], 2, v[94:95]
	v_lshl_add_u64 v[94:95], v[94:95], 0, s[84:85]
	global_store_dword v[94:95], v2, off

;     __device__ __forceinline__ void operator()(const f32x4 (&acc)[2][2][4][2], const Unit& u, int wr, int wc, int fr, int fq) const {
;     ...
;                 for (int mm = 0; mm < NPF; ++mm) { const int row = row0 + ai * HALF + (NPF * mp + mm) * 16;
; #pragma unroll
;                     for (int bj = 0; bj < 2; ++bj) { const size_t off = (size_t)row * 1024 + col0 + bj * HALF; hv[mm][bj] = *(const u32x4*)(hin + off); if (GATED) pv[mm][bj] = *(const u32x4*)(pl + off); } }
; #pragma unroll
;                 for (int mm = 0; mm < NPF; ++mm) { const int m = NPF * mp + mm, row = row0 + ai * HALF + m * 16;
;                     float r = 1.f; if (GATED) r = (u.ui < 8) ? rtab[u.ui * 256 + wr * 64 + fr + ai * HALF + m * 16] : rinv16(ssq_in, row, 1.0f / 1024.0f);
;                     if (MID) r = rtab[u.ui * 512 + wr * 64 + fr + ai * HALF + m * 16];
;                     float sq = 0.f;
; #pragma unroll
;                     for (int bj = 0; bj < 2; ++bj) { const size_t off = (size_t)row * 1024 + col0 + bj * HALF;
;                         f32x4 a0 = acc[ai][bj][m][0], a1 = acc[ai][bj][m][1]; const u32x4 hq = hv[mm][bj];
;                         f32x4 x0 = (f32x4){bf_lo(hq.x), bf_hi(hq.x), bf_lo(hq.y), bf_hi(hq.y)}, x1 = (f32x4){bf_lo(hq.z), bf_hi(hq.z), bf_lo(hq.w), bf_hi(hq.w)};
;                         if (MID) { a0 = a0 * r; a1 = a1 * r; }
;                         if (GATED) { const u32x4 p4 = pv[mm][bj];
;                             a0[0] = sigmoid_f(a0[0] * r) * bf_lo(p4.x); a0[1] = sigmoid_f(a0[1] * r) * bf_hi(p4.x); a0[2] = sigmoid_f(a0[2] * r) * bf_lo(p4.y); a0[3] = sigmoid_f(a0[3] * r) * bf_hi(p4.y);
;                             a1[0] = sigmoid_f(a1[0] * r) * bf_lo(p4.z); a1[1] = sigmoid_f(a1[1] * r) * bf_hi(p4.z); a1[2] = sigmoid_f(a1[2] * r) * bf_lo(p4.w); a1[3] = sigmoid_f(a1[3] * r) * bf_hi(p4.w); }
;                         x0 = x0 + a0; x1 = x1 + a1;
;                         u32x4 w; w.x = cvt_pk_bf16(x0[0], x0[1]); w.y = cvt_pk_bf16(x0[2], x0[3]); w.z = cvt_pk_bf16(x1[0], x1[1]); w.w = cvt_pk_bf16(x1[2], x1[3]);
;                         if (!dry) *(u32x4*)(hb + off) = w; else asm volatile("" :: "v"(w.x), "v"(w.y), "v"(w.z), "v"(w.w));
;                         sq += ((x0[0] * x0[0] + x0[1] * x0[1]) + (x0[2] * x0[2] + x0[3] * x0[3])) + ((x1[0] * x1[0] + x1[1] * x1[1]) + (x1[2] * x1[2] + x1[3] * x1[3])); }
.LBB0_1679:
	s_or_b64 exec, exec, s[34:35]
	v_add_u32_e32 v90, 0x80, v150
	v_ashrrev_i32_e32 v91, 31, v90
	v_lshlrev_b64 v[100:101], 11, v[90:91]
	v_lshl_add_u64 v[78:79], v[152:153], 0, v[100:101]
	v_add_u32_e32 v86, 0x90, v150
	v_ashrrev_i32_e32 v87, 31, v86
	v_lshlrev_b64 v[88:89], 11, v[86:87]
	v_lshl_add_u64 v[78:79], v[152:153], 0, v[88:89]
	v_lshl_add_u64 v[100:101], s[14:15], 0, v[100:101]
	v_lshl_add_u64 v[100:101], v[4:5], 1, v[100:101]
	s_waitcnt vmcnt(6)
	v_mov_b64_e32 v[92:93], v[180:181]
	v_mov_b64_e32 v[94:95], v[182:183]
	v_mov_b64_e32 v[96:97], v[184:185]
	v_mov_b64_e32 v[98:99], v[186:187]
	v_mov_b64_e32 v[82:83], v[188:189]
	v_mov_b64_e32 v[84:85], v[190:191]
	v_mov_b64_e32 v[78:79], v[192:193]
	v_mov_b64_e32 v[80:81], v[194:195]
	v_add_u32_e32 v196, 160, v150
	v_ashrrev_i32_e32 v197, 31, v196
	v_lshlrev_b64 v[196:197], 11, v[196:197]
	v_lshl_add_u64 v[196:197], v[152:153], 0, v[196:197]
	global_load_dwordx4 v[180:183], v[196:197], off
	global_load_dwordx4 v[184:187], v[196:197], off offset:256
	v_add_u32_e32 v198, 176, v150
	v_ashrrev_i32_e32 v199, 31, v198
	v_lshlrev_b64 v[198:199], 11, v[198:199]
	v_lshl_add_u64 v[198:199], v[152:153], 0, v[198:199]
	global_load_dwordx4 v[188:191], v[198:199], off
	global_load_dwordx4 v[192:195], v[198:199], off offset:256
	v_lshlrev_b32_e32 v102, 16, v92
	v_and_b32_e32 v103, 0xffff0000, v92
	v_lshlrev_b32_e32 v92, 16, v93
	v_and_b32_e32 v93, 0xffff0000, v93
	v_lshlrev_b32_e32 v104, 16, v94
	v_and_b32_e32 v105, 0xffff0000, v94
	v_lshlrev_b32_e32 v94, 16, v95
	v_and_b32_e32 v95, 0xffff0000, v95
	v_pk_add_f32 v[76:77], v[76:77], v[92:93]
	v_pk_add_f32 v[74:75], v[74:75], v[102:103]
	v_pk_add_f32 v[92:93], v[72:73], v[94:95]
	v_pk_add_f32 v[94:95], v[70:71], v[104:105]
	v_cvt_pk_bf16_f32 v70, v74, v75
	v_cvt_pk_bf16_f32 v71, v76, v77
	v_mul_f32_e32 v2, v75, v75
	v_cvt_pk_bf16_f32 v72, v94, v95
	v_cvt_pk_bf16_f32 v73, v92, v93
	global_store_dwordx4 v[100:101], v[70:73], off
	v_fmac_f32_e32 v2, v74, v74
	v_lshlrev_b32_e32 v74, 16, v98
	v_mul_f32_e32 v70, v77, v77
	v_fmac_f32_e32 v70, v76, v76
	v_add_f32_e32 v2, v2, v70
	v_mul_f32_e32 v70, v95, v95
	v_mul_f32_e32 v71, v93, v93
	v_fmac_f32_e32 v70, v94, v94
	v_fmac_f32_e32 v71, v92, v92
	v_add_f32_e32 v70, v70, v71
	v_add_f32_e32 v2, v2, v70
	v_lshlrev_b32_e32 v70, 16, v96
	v_and_b32_e32 v71, 0xffff0000, v96
	v_lshlrev_b32_e32 v72, 16, v97
	v_and_b32_e32 v73, 0xffff0000, v97
	v_and_b32_e32 v75, 0xffff0000, v98
	v_lshlrev_b32_e32 v76, 16, v99
	v_and_b32_e32 v77, 0xffff0000, v99
	v_pk_add_f32 v[68:69], v[68:69], v[72:73]
	v_pk_add_f32 v[66:67], v[66:67], v[70:71]
	v_pk_add_f32 v[72:73], v[62:63], v[74:75]
	v_cvt_pk_bf16_f32 v62, v66, v67
	v_cvt_pk_bf16_f32 v63, v68, v69
	v_pk_add_f32 v[70:71], v[64:65], v[76:77]
	v_cvt_pk_bf16_f32 v64, v72, v73
	s_nop 0
	v_cvt_pk_bf16_f32 v65, v70, v71
	global_store_dwordx4 v[100:101], v[62:65], off offset:256
	s_nop 1
	v_mul_f32_e32 v62, v67, v67
	v_mul_f32_e32 v63, v69, v69
	v_fmac_f32_e32 v62, v66, v66
	v_fmac_f32_e32 v63, v68, v68
	v_add_f32_e32 v62, v62, v63
	v_mul_f32_e32 v63, v73, v73
	v_mul_f32_e32 v64, v71, v71
	v_fmac_f32_e32 v63, v72, v72
	v_fmac_f32_e32 v64, v70, v70
	v_add_f32_e32 v63, v63, v64
	v_add_f32_e32 v62, v62, v63
	v_add_f32_e32 v2, v2, v62
	v_mov_b32_e32 v62, v2
	v_mov_b32_e32 v63, v2
	s_nop 1
	v_permlane16_swap_b32_e32 v62, v63
	v_cndmask_b32_e64 v62, v62, v63, s[0:1]
	v_add_f32_e32 v2, v2, v62
	v_mov_b32_e32 v62, v2
	v_mov_b32_e32 v63, v2
	s_nop 1
	v_permlane32_swap_b32_e32 v62, v63
	s_and_saveexec_b64 s[34:35], s[2:3]
	s_cbranch_execz .LBB0_1681
	v_and_b32_e32 v64, 32, v247
	v_cmp_eq_u32_e32 vcc, 0, v64
	s_lshl_b32 s84, s81, 2
	s_nop 0
	v_cndmask_b32_e32 v62, v62, v63, vcc
	v_add_f32_e32 v2, v2, v62
	v_lshlrev_b64 v[62:63], 6, v[90:91]
	v_lshl_add_u64 v[62:63], s[16:17], 0, v[62:63]
	v_lshl_add_u64 v[62:63], s[6:7], 2, v[62:63]
	v_lshl_add_u64 v[62:63], v[62:63], 0, s[84:85]
	global_store_dword v[62:63], v2, off

;     __device__ __forceinline__ void operator()(const f32x4 (&acc)[2][2][4][2], const Unit& u, int wr, int wc, int fr, int fq) const {
;     ...
;                 for (int mm = 0; mm < NPF; ++mm) { const int row = row0 + ai * HALF + (NPF * mp + mm) * 16;
; #pragma unroll
;                     for (int bj = 0; bj < 2; ++bj) { const size_t off = (size_t)row * 1024 + col0 + bj * HALF; hv[mm][bj] = *(const u32x4*)(hin + off); if (GATED) pv[mm][bj] = *(const u32x4*)(pl + off); } }
; #pragma unroll
;                 for (int mm = 0; mm < NPF; ++mm) { const int m = NPF * mp + mm, row = row0 + ai * HALF + m * 16;
;                     float r = 1.f; if (GATED) r = (u.ui < 8) ? rtab[u.ui * 256 + wr * 64 + fr + ai * HALF + m * 16] : rinv16(ssq_in, row, 1.0f / 1024.0f);
;                     if (MID) r = rtab[u.ui * 512 + wr * 64 + fr + ai * HALF + m * 16];
;                     float sq = 0.f;
; #pragma unroll
;                     for (int bj = 0; bj < 2; ++bj) { const size_t off = (size_t)row * 1024 + col0 + bj * HALF;
;                         f32x4 a0 = acc[ai][bj][m][0], a1 = acc[ai][bj][m][1]; const u32x4 hq = hv[mm][bj];
;                         f32x4 x0 = (f32x4){bf_lo(hq.x), bf_hi(hq.x), bf_lo(hq.y), bf_hi(hq.y)}, x1 = (f32x4){bf_lo(hq.z), bf_hi(hq.z), bf_lo(hq.w), bf_hi(hq.w)};
;                         if (MID) { a0 = a0 * r; a1 = a1 * r; }
;                         if (GATED) { const u32x4 p4 = pv[mm][bj];
;                             a0[0] = sigmoid_f(a0[0] * r) * bf_lo(p4.x); a0[1] = sigmoid_f(a0[1] * r) * bf_hi(p4.x); a0[2] = sigmoid_f(a0[2] * r) * bf_lo(p4.y); a0[3] = sigmoid_f(a0[3] * r) * bf_hi(p4.y);
;                             a1[0] = sigmoid_f(a1[0] * r) * bf_lo(p4.z); a1[1] = sigmoid_f(a1[1] * r) * bf_hi(p4.z); a1[2] = sigmoid_f(a1[2] * r) * bf_lo(p4.w); a1[3] = sigmoid_f(a1[3] * r) * bf_hi(p4.w); }
;                         x0 = x0 + a0; x1 = x1 + a1;
;                         u32x4 w; w.x = cvt_pk_bf16(x0[0], x0[1]); w.y = cvt_pk_bf16(x0[2], x0[3]); w.z = cvt_pk_bf16(x1[0], x1[1]); w.w = cvt_pk_bf16(x1[2], x1[3]);
;                         if (!dry) *(u32x4*)(hb + off) = w; else asm volatile("" :: "v"(w.x), "v"(w.y), "v"(w.z), "v"(w.w));
;                         sq += ((x0[0] * x0[0] + x0[1] * x0[1]) + (x0[2] * x0[2] + x0[3] * x0[3])) + ((x1[0] * x1[0] + x1[1] * x1[1]) + (x1[2] * x1[2] + x1[3] * x1[3])); }
.LBB0_1683:
	s_or_b64 exec, exec, s[34:35]
	v_add_u32_e32 v58, 0xa0, v150
	v_ashrrev_i32_e32 v59, 31, v58
	v_lshlrev_b64 v[68:69], 11, v[58:59]
	v_lshl_add_u64 v[46:47], v[152:153], 0, v[68:69]
	v_add_u32_e32 v54, 0xb0, v150
	v_ashrrev_i32_e32 v55, 31, v54
	v_lshlrev_b64 v[56:57], 11, v[54:55]
	v_lshl_add_u64 v[46:47], v[152:153], 0, v[56:57]
	v_lshl_add_u64 v[68:69], s[14:15], 0, v[68:69]
	v_lshl_add_u64 v[68:69], v[4:5], 1, v[68:69]
	s_waitcnt vmcnt(6)
	v_mov_b64_e32 v[60:61], v[180:181]
	v_mov_b64_e32 v[62:63], v[182:183]
	v_mov_b64_e32 v[64:65], v[184:185]
	v_mov_b64_e32 v[66:67], v[186:187]
	v_mov_b64_e32 v[50:51], v[188:189]
	v_mov_b64_e32 v[52:53], v[190:191]
	v_mov_b64_e32 v[46:47], v[192:193]
	v_mov_b64_e32 v[48:49], v[194:195]
	v_lshlrev_b32_e32 v70, 16, v60
	v_and_b32_e32 v71, 0xffff0000, v60
	v_lshlrev_b32_e32 v60, 16, v61
	v_and_b32_e32 v61, 0xffff0000, v61
	v_lshlrev_b32_e32 v72, 16, v62
	v_and_b32_e32 v73, 0xffff0000, v62
	v_lshlrev_b32_e32 v62, 16, v63
	v_and_b32_e32 v63, 0xffff0000, v63
	v_pk_add_f32 v[44:45], v[44:45], v[60:61]
	v_pk_add_f32 v[42:43], v[42:43], v[70:71]
	v_pk_add_f32 v[60:61], v[40:41], v[62:63]
	v_pk_add_f32 v[62:63], v[38:39], v[72:73]
	v_cvt_pk_bf16_f32 v38, v42, v43
	v_cvt_pk_bf16_f32 v39, v44, v45
	v_mul_f32_e32 v2, v43, v43
	v_cvt_pk_bf16_f32 v40, v62, v63
	v_cvt_pk_bf16_f32 v41, v60, v61
	global_store_dwordx4 v[68:69], v[38:41], off
	v_fmac_f32_e32 v2, v42, v42
	v_lshlrev_b32_e32 v42, 16, v66
	v_mul_f32_e32 v38, v45, v45
	v_fmac_f32_e32 v38, v44, v44
	v_add_f32_e32 v2, v2, v38
	v_mul_f32_e32 v38, v63, v63
	v_mul_f32_e32 v39, v61, v61
	v_fmac_f32_e32 v38, v62, v62
	v_fmac_f32_e32 v39, v60, v60
	v_add_f32_e32 v38, v38, v39
	v_add_f32_e32 v2, v2, v38
	v_lshlrev_b32_e32 v38, 16, v64
	v_and_b32_e32 v39, 0xffff0000, v64
	v_lshlrev_b32_e32 v40, 16, v65
	v_and_b32_e32 v41, 0xffff0000, v65
	v_and_b32_e32 v43, 0xffff0000, v66
	v_lshlrev_b32_e32 v44, 16, v67
	v_and_b32_e32 v45, 0xffff0000, v67
	v_pk_add_f32 v[36:37], v[36:37], v[40:41]
	v_pk_add_f32 v[34:35], v[34:35], v[38:39]
	v_pk_add_f32 v[40:41], v[30:31], v[42:43]
	v_cvt_pk_bf16_f32 v30, v34, v35
	v_cvt_pk_bf16_f32 v31, v36, v37
	v_pk_add_f32 v[38:39], v[32:33], v[44:45]
	v_cvt_pk_bf16_f32 v32, v40, v41
	s_nop 0
	v_cvt_pk_bf16_f32 v33, v38, v39
	global_store_dwordx4 v[68:69], v[30:33], off offset:256
	s_nop 1
	v_mul_f32_e32 v30, v35, v35
	v_mul_f32_e32 v31, v37, v37
	v_fmac_f32_e32 v30, v34, v34
	v_fmac_f32_e32 v31, v36, v36
	v_add_f32_e32 v30, v30, v31
	v_mul_f32_e32 v31, v41, v41
	v_mul_f32_e32 v32, v39, v39
	v_fmac_f32_e32 v31, v40, v40
	v_fmac_f32_e32 v32, v38, v38
	v_add_f32_e32 v31, v31, v32
	v_add_f32_e32 v30, v30, v31
	v_add_f32_e32 v2, v2, v30
	v_mov_b32_e32 v30, v2
	v_mov_b32_e32 v31, v2
	s_nop 1
	v_permlane16_swap_b32_e32 v30, v31
	v_cndmask_b32_e64 v30, v30, v31, s[0:1]
	v_add_f32_e32 v2, v2, v30
	v_mov_b32_e32 v30, v2
	v_mov_b32_e32 v31, v2
	s_nop 1
	v_permlane32_swap_b32_e32 v30, v31
	s_and_saveexec_b64 s[34:35], s[2:3]
	s_cbranch_execz .LBB0_1685
	v_and_b32_e32 v32, 32, v247
	v_cmp_eq_u32_e32 vcc, 0, v32
	s_lshl_b32 s84, s81, 2
	s_nop 0
	v_cndmask_b32_e32 v30, v30, v31, vcc
	v_add_f32_e32 v2, v2, v30
	v_lshlrev_b64 v[30:31], 6, v[58:59]
	v_lshl_add_u64 v[30:31], s[16:17], 0, v[30:31]
	v_lshl_add_u64 v[30:31], s[6:7], 2, v[30:31]
	v_lshl_add_u64 v[30:31], v[30:31], 0, s[84:85]
	global_store_dword v[30:31], v2, off
